# top-k: final selection words written with v_writelane (3 instrs per tile instead of 7), skipping tiles beyond the row; key transform skipped (zero fill) for key groups beyond the row
# speedup vs baseline: 1.0286x; 1.0018x over previous
; __device__ __forceinline__ void b1_phase(const bf16* QI, const bf16* KI, const float* WI, float* SCRb  , unsigned long long* MASK,
;                                          LAS unsigned char* lds, int vcu, int G, int tid) {
;     ...
; #pragma unroll
;             for (int j = 0; j < 64; ++j) { unsigned key = 0u; if (j < ntile) { const float f = srow[j * 64] + 0.0f; const unsigned bts = __float_as_uint(f); key = bts ^ ((bts >> 31) ? 0xFFFFFFFFu : 0x80000000u); } uu[j] = key; }
.Ltopk_loads_done:
	s_waitcnt vmcnt(0)
	v_add_f32_e32 v6, 0, v6
	v_add_f32_e32 v0, 0, v0
	v_ashrrev_i32_e32 v2, 31, v6
	v_ashrrev_i32_e32 v3, 31, v0
	v_or_b32_e32 v2, v239, v2
	v_or_b32_e32 v3, v239, v3
	v_xor_b32_e32 v6, v2, v6
	v_xor_b32_e32 v0, v3, v0
	s_cmp_ge_u32 s99, 1
	s_cselect_b32 s98, -1, 0
	v_and_b32_e32 v6, s98, v6
	s_cmp_ge_u32 s99, 2
	s_cselect_b32 s98, -1, 0
	v_and_b32_e32 v0, s98, v0
	v_add_f32_e32 v8, 0, v8
	v_add_f32_e32 v4, 0, v4
	v_ashrrev_i32_e32 v2, 31, v8
	v_ashrrev_i32_e32 v3, 31, v4
	v_or_b32_e32 v2, v239, v2
	v_or_b32_e32 v3, v239, v3
	v_xor_b32_e32 v8, v2, v8
	v_xor_b32_e32 v4, v3, v4
	s_cmp_ge_u32 s99, 3
	s_cselect_b32 s98, -1, 0
	v_and_b32_e32 v8, s98, v8
	s_cmp_ge_u32 s99, 4
	s_cselect_b32 s98, -1, 0
	v_and_b32_e32 v4, s98, v4
	v_add_f32_e32 v10, 0, v10
	v_add_f32_e32 v5, 0, v5
	v_ashrrev_i32_e32 v2, 31, v10
	v_ashrrev_i32_e32 v3, 31, v5
	v_or_b32_e32 v2, v239, v2
	v_or_b32_e32 v3, v239, v3
	v_xor_b32_e32 v10, v2, v10
	v_xor_b32_e32 v5, v3, v5
	s_cmp_ge_u32 s99, 5
	s_cselect_b32 s98, -1, 0
	v_and_b32_e32 v10, s98, v10
	s_cmp_ge_u32 s99, 6
	s_cselect_b32 s98, -1, 0
	v_and_b32_e32 v5, s98, v5
	v_add_f32_e32 v12, 0, v12
	v_add_f32_e32 v7, 0, v7
	v_ashrrev_i32_e32 v2, 31, v12
	v_ashrrev_i32_e32 v3, 31, v7
	v_or_b32_e32 v2, v239, v2
	v_or_b32_e32 v3, v239, v3
	v_xor_b32_e32 v12, v2, v12
	v_xor_b32_e32 v7, v3, v7
	s_cmp_ge_u32 s99, 7
	s_cselect_b32 s98, -1, 0
	v_and_b32_e32 v12, s98, v12
	s_cmp_ge_u32 s99, 8
	s_cselect_b32 s98, -1, 0
	v_and_b32_e32 v7, s98, v7
	v_add_f32_e32 v14, 0, v14
	v_add_f32_e32 v9, 0, v9
	v_ashrrev_i32_e32 v2, 31, v14
	v_ashrrev_i32_e32 v3, 31, v9
	v_or_b32_e32 v2, v239, v2
	v_or_b32_e32 v3, v239, v3
	v_xor_b32_e32 v14, v2, v14
	v_xor_b32_e32 v9, v3, v9
	s_cmp_ge_u32 s99, 9
	s_cselect_b32 s98, -1, 0
	v_and_b32_e32 v14, s98, v14
	s_cmp_ge_u32 s99, 10
	s_cselect_b32 s98, -1, 0
	v_and_b32_e32 v9, s98, v9
	v_add_f32_e32 v15, 0, v15
	v_add_f32_e32 v11, 0, v11
	v_ashrrev_i32_e32 v2, 31, v15
	v_ashrrev_i32_e32 v3, 31, v11
	v_or_b32_e32 v2, v239, v2
	v_or_b32_e32 v3, v239, v3
	v_xor_b32_e32 v15, v2, v15
	v_xor_b32_e32 v11, v3, v11
	s_cmp_ge_u32 s99, 11
	s_cselect_b32 s98, -1, 0
	v_and_b32_e32 v15, s98, v15
	s_cmp_ge_u32 s99, 12
	s_cselect_b32 s98, -1, 0
	v_and_b32_e32 v11, s98, v11
	v_add_f32_e32 v17, 0, v17
	v_add_f32_e32 v13, 0, v13
	v_ashrrev_i32_e32 v2, 31, v17
	v_ashrrev_i32_e32 v3, 31, v13
	v_or_b32_e32 v2, v239, v2
	v_or_b32_e32 v3, v239, v3
	v_xor_b32_e32 v17, v2, v17
	v_xor_b32_e32 v13, v3, v13
	s_cmp_ge_u32 s99, 13
	s_cselect_b32 s98, -1, 0
	v_and_b32_e32 v17, s98, v17
	s_cmp_ge_u32 s99, 14
	s_cselect_b32 s98, -1, 0
	v_and_b32_e32 v13, s98, v13
	v_add_f32_e32 v18, 0, v18
	v_ashrrev_i32_e32 v2, 31, v18
	v_or_b32_e32 v2, v239, v2
	v_xor_b32_e32 v18, v2, v18
	s_cmp_ge_u32 s99, 15
	s_cselect_b32 s98, -1, 0
	v_and_b32_e32 v18, s98, v18
	s_cmp_lt_u32 s99, 16
	s_cbranch_scc1 .Ltk_zero_1
	v_add_f32_e32 v16, 0, v16
	v_add_f32_e32 v20, 0, v20
	v_ashrrev_i32_e32 v2, 31, v16
	v_ashrrev_i32_e32 v3, 31, v20
	v_or_b32_e32 v2, v239, v2
	v_or_b32_e32 v3, v239, v3
	v_xor_b32_e32 v16, v2, v16
	v_xor_b32_e32 v20, v3, v20
	s_cmp_ge_u32 s99, 16
	s_cselect_b32 s98, -1, 0
	v_and_b32_e32 v16, s98, v16
	s_cmp_ge_u32 s99, 17
	s_cselect_b32 s98, -1, 0
	v_and_b32_e32 v20, s98, v20
	v_add_f32_e32 v19, 0, v19
	v_add_f32_e32 v22, 0, v22
	v_ashrrev_i32_e32 v2, 31, v19
	v_ashrrev_i32_e32 v3, 31, v22
	v_or_b32_e32 v2, v239, v2
	v_or_b32_e32 v3, v239, v3
	v_xor_b32_e32 v19, v2, v19
	v_xor_b32_e32 v22, v3, v22
	s_cmp_ge_u32 s99, 18
	s_cselect_b32 s98, -1, 0
	v_and_b32_e32 v19, s98, v19
	s_cmp_ge_u32 s99, 19
	s_cselect_b32 s98, -1, 0
	v_and_b32_e32 v22, s98, v22
	v_add_f32_e32 v21, 0, v21
	v_add_f32_e32 v24, 0, v24
	v_ashrrev_i32_e32 v2, 31, v21
	v_ashrrev_i32_e32 v3, 31, v24
	v_or_b32_e32 v2, v239, v2
	v_or_b32_e32 v3, v239, v3
	v_xor_b32_e32 v21, v2, v21
	v_xor_b32_e32 v24, v3, v24
	s_cmp_ge_u32 s99, 20
	s_cselect_b32 s98, -1, 0
	v_and_b32_e32 v21, s98, v21
	s_cmp_ge_u32 s99, 21
	s_cselect_b32 s98, -1, 0
	v_and_b32_e32 v24, s98, v24
	v_add_f32_e32 v23, 0, v23
	v_add_f32_e32 v26, 0, v26
	v_ashrrev_i32_e32 v2, 31, v23
	v_ashrrev_i32_e32 v3, 31, v26
	v_or_b32_e32 v2, v239, v2
	v_or_b32_e32 v3, v239, v3
	v_xor_b32_e32 v23, v2, v23
	v_xor_b32_e32 v26, v3, v26
	s_cmp_ge_u32 s99, 22
	s_cselect_b32 s98, -1, 0
	v_and_b32_e32 v23, s98, v23
	s_cmp_ge_u32 s99, 23
	s_cselect_b32 s98, -1, 0
	v_and_b32_e32 v26, s98, v26
	v_add_f32_e32 v25, 0, v25
	v_add_f32_e32 v28, 0, v28
	v_ashrrev_i32_e32 v2, 31, v25
	v_ashrrev_i32_e32 v3, 31, v28
	v_or_b32_e32 v2, v239, v2
	v_or_b32_e32 v3, v239, v3
	v_xor_b32_e32 v25, v2, v25
	v_xor_b32_e32 v28, v3, v28
	s_cmp_ge_u32 s99, 24
	s_cselect_b32 s98, -1, 0
	v_and_b32_e32 v25, s98, v25
	s_cmp_ge_u32 s99, 25
	s_cselect_b32 s98, -1, 0
	v_and_b32_e32 v28, s98, v28
	v_add_f32_e32 v27, 0, v27
	v_add_f32_e32 v30, 0, v30
	v_ashrrev_i32_e32 v2, 31, v27
	v_ashrrev_i32_e32 v3, 31, v30
	v_or_b32_e32 v2, v239, v2
	v_or_b32_e32 v3, v239, v3
	v_xor_b32_e32 v27, v2, v27
	v_xor_b32_e32 v30, v3, v30
	s_cmp_ge_u32 s99, 26
	s_cselect_b32 s98, -1, 0
	v_and_b32_e32 v27, s98, v27
	s_cmp_ge_u32 s99, 27
	s_cselect_b32 s98, -1, 0
	v_and_b32_e32 v30, s98, v30
	v_add_f32_e32 v29, 0, v29
	v_add_f32_e32 v32, 0, v32
	v_ashrrev_i32_e32 v2, 31, v29
	v_ashrrev_i32_e32 v3, 31, v32
	v_or_b32_e32 v2, v239, v2
	v_or_b32_e32 v3, v239, v3
	v_xor_b32_e32 v29, v2, v29
	v_xor_b32_e32 v32, v3, v32
	s_cmp_ge_u32 s99, 28
	s_cselect_b32 s98, -1, 0
	v_and_b32_e32 v29, s98, v29
	s_cmp_ge_u32 s99, 29
	s_cselect_b32 s98, -1, 0
	v_and_b32_e32 v32, s98, v32
	v_add_f32_e32 v31, 0, v31
	v_add_f32_e32 v34, 0, v34
	v_ashrrev_i32_e32 v2, 31, v31
	v_ashrrev_i32_e32 v3, 31, v34
	v_or_b32_e32 v2, v239, v2
	v_or_b32_e32 v3, v239, v3
	v_xor_b32_e32 v31, v2, v31
	v_xor_b32_e32 v34, v3, v34
	s_cmp_ge_u32 s99, 30
	s_cselect_b32 s98, -1, 0
	v_and_b32_e32 v31, s98, v31
	s_cmp_ge_u32 s99, 31
	s_cselect_b32 s98, -1, 0
	v_and_b32_e32 v34, s98, v34
	s_cmp_lt_u32 s99, 32
	s_cbranch_scc1 .Ltk_zero_2
; __device__ __forceinline__ void b1_phase(const bf16* QI, const bf16* KI, const float* WI, float* SCRb  , unsigned long long* MASK,
;                                          LAS unsigned char* lds, int vcu, int G, int tid) {
;     ...
; #pragma unroll
;             for (int j = 0; j < 64; ++j) { unsigned key = 0u; if (j < ntile) { const float f = srow[j * 64] + 0.0f; const unsigned bts = __float_as_uint(f); key = bts ^ ((bts >> 31) ? 0xFFFFFFFFu : 0x80000000u); } uu[j] = key; }
	v_add_f32_e32 v33, 0, v33
	v_add_f32_e32 v37, 0, v37
	v_ashrrev_i32_e32 v2, 31, v33
	v_ashrrev_i32_e32 v3, 31, v37
	v_or_b32_e32 v2, v239, v2
	v_or_b32_e32 v3, v239, v3
	v_xor_b32_e32 v33, v2, v33
	v_xor_b32_e32 v37, v3, v37
	s_cmp_ge_u32 s99, 32
	s_cselect_b32 s98, -1, 0
	v_and_b32_e32 v33, s98, v33
	s_cmp_ge_u32 s99, 33
	s_cselect_b32 s98, -1, 0
	v_and_b32_e32 v37, s98, v37
	v_add_f32_e32 v35, 0, v35
	v_add_f32_e32 v39, 0, v39
	v_ashrrev_i32_e32 v2, 31, v35
	v_ashrrev_i32_e32 v3, 31, v39
	v_or_b32_e32 v2, v239, v2
	v_or_b32_e32 v3, v239, v3
	v_xor_b32_e32 v35, v2, v35
	v_xor_b32_e32 v39, v3, v39
	s_cmp_ge_u32 s99, 34
	s_cselect_b32 s98, -1, 0
	v_and_b32_e32 v35, s98, v35
	s_cmp_ge_u32 s99, 35
	s_cselect_b32 s98, -1, 0
	v_and_b32_e32 v39, s98, v39
	v_add_f32_e32 v36, 0, v36
	v_add_f32_e32 v41, 0, v41
	v_ashrrev_i32_e32 v2, 31, v36
	v_ashrrev_i32_e32 v3, 31, v41
	v_or_b32_e32 v2, v239, v2
	v_or_b32_e32 v3, v239, v3
	v_xor_b32_e32 v36, v2, v36
	v_xor_b32_e32 v41, v3, v41
	s_cmp_ge_u32 s99, 36
	s_cselect_b32 s98, -1, 0
	v_and_b32_e32 v36, s98, v36
	s_cmp_ge_u32 s99, 37
	s_cselect_b32 s98, -1, 0
	v_and_b32_e32 v41, s98, v41
	v_add_f32_e32 v38, 0, v38
	v_add_f32_e32 v43, 0, v43
	v_ashrrev_i32_e32 v2, 31, v38
	v_ashrrev_i32_e32 v3, 31, v43
	v_or_b32_e32 v2, v239, v2
	v_or_b32_e32 v3, v239, v3
	v_xor_b32_e32 v38, v2, v38
	v_xor_b32_e32 v43, v3, v43
	s_cmp_ge_u32 s99, 38
	s_cselect_b32 s98, -1, 0
	v_and_b32_e32 v38, s98, v38
	s_cmp_ge_u32 s99, 39
	s_cselect_b32 s98, -1, 0
	v_and_b32_e32 v43, s98, v43
	v_add_f32_e32 v40, 0, v40
	v_add_f32_e32 v45, 0, v45
	v_ashrrev_i32_e32 v2, 31, v40
	v_ashrrev_i32_e32 v3, 31, v45
	v_or_b32_e32 v2, v239, v2
	v_or_b32_e32 v3, v239, v3
	v_xor_b32_e32 v40, v2, v40
	v_xor_b32_e32 v45, v3, v45
	s_cmp_ge_u32 s99, 40
	s_cselect_b32 s98, -1, 0
	v_and_b32_e32 v40, s98, v40
	s_cmp_ge_u32 s99, 41
	s_cselect_b32 s98, -1, 0
	v_and_b32_e32 v45, s98, v45
	v_add_f32_e32 v42, 0, v42
	v_add_f32_e32 v47, 0, v47
	v_ashrrev_i32_e32 v2, 31, v42
	v_ashrrev_i32_e32 v3, 31, v47
	v_or_b32_e32 v2, v239, v2
	v_or_b32_e32 v3, v239, v3
	v_xor_b32_e32 v42, v2, v42
	v_xor_b32_e32 v47, v3, v47
	s_cmp_ge_u32 s99, 42
	s_cselect_b32 s98, -1, 0
	v_and_b32_e32 v42, s98, v42
	s_cmp_ge_u32 s99, 43
	s_cselect_b32 s98, -1, 0
	v_and_b32_e32 v47, s98, v47
	v_add_f32_e32 v44, 0, v44
	v_add_f32_e32 v49, 0, v49
	v_ashrrev_i32_e32 v2, 31, v44
	v_ashrrev_i32_e32 v3, 31, v49
	v_or_b32_e32 v2, v239, v2
	v_or_b32_e32 v3, v239, v3
	v_xor_b32_e32 v44, v2, v44
	v_xor_b32_e32 v49, v3, v49
	s_cmp_ge_u32 s99, 44
	s_cselect_b32 s98, -1, 0
	v_and_b32_e32 v44, s98, v44
	s_cmp_ge_u32 s99, 45
	s_cselect_b32 s98, -1, 0
	v_and_b32_e32 v49, s98, v49
	v_add_f32_e32 v46, 0, v46
	v_add_f32_e32 v51, 0, v51
	v_ashrrev_i32_e32 v2, 31, v46
	v_ashrrev_i32_e32 v3, 31, v51
	v_or_b32_e32 v2, v239, v2
	v_or_b32_e32 v3, v239, v3
	v_xor_b32_e32 v46, v2, v46
	v_xor_b32_e32 v51, v3, v51
	s_cmp_ge_u32 s99, 46
	s_cselect_b32 s98, -1, 0
	v_and_b32_e32 v46, s98, v46
	s_cmp_ge_u32 s99, 47
	s_cselect_b32 s98, -1, 0
	v_and_b32_e32 v51, s98, v51
	s_cmp_lt_u32 s99, 48
	s_cbranch_scc1 .Ltk_zero_3
	v_add_f32_e32 v48, 0, v48
	v_add_f32_e32 v53, 0, v53
	v_ashrrev_i32_e32 v2, 31, v48
	v_ashrrev_i32_e32 v3, 31, v53
	v_or_b32_e32 v2, v239, v2
	v_or_b32_e32 v3, v239, v3
	v_xor_b32_e32 v48, v2, v48
	v_xor_b32_e32 v53, v3, v53
	s_cmp_ge_u32 s99, 48
	s_cselect_b32 s98, -1, 0
	v_and_b32_e32 v48, s98, v48
	s_cmp_ge_u32 s99, 49
	s_cselect_b32 s98, -1, 0
	v_and_b32_e32 v53, s98, v53
	v_add_f32_e32 v50, 0, v50
	v_add_f32_e32 v55, 0, v55
	v_ashrrev_i32_e32 v2, 31, v50
	v_ashrrev_i32_e32 v3, 31, v55
	v_or_b32_e32 v2, v239, v2
	v_or_b32_e32 v3, v239, v3
	v_xor_b32_e32 v50, v2, v50
	v_xor_b32_e32 v55, v3, v55
	s_cmp_ge_u32 s99, 50
	s_cselect_b32 s98, -1, 0
	v_and_b32_e32 v50, s98, v50
	s_cmp_ge_u32 s99, 51
	s_cselect_b32 s98, -1, 0
	v_and_b32_e32 v55, s98, v55
	v_add_f32_e32 v52, 0, v52
	v_add_f32_e32 v57, 0, v57
	v_ashrrev_i32_e32 v2, 31, v52
	v_ashrrev_i32_e32 v3, 31, v57
	v_or_b32_e32 v2, v239, v2
	v_or_b32_e32 v3, v239, v3
	v_xor_b32_e32 v52, v2, v52
	v_xor_b32_e32 v57, v3, v57
	s_cmp_ge_u32 s99, 52
	s_cselect_b32 s98, -1, 0
	v_and_b32_e32 v52, s98, v52
	s_cmp_ge_u32 s99, 53
	s_cselect_b32 s98, -1, 0
	v_and_b32_e32 v57, s98, v57
	v_add_f32_e32 v54, 0, v54
	v_add_f32_e32 v59, 0, v59
	v_ashrrev_i32_e32 v2, 31, v54
	v_ashrrev_i32_e32 v3, 31, v59
	v_or_b32_e32 v2, v239, v2
	v_or_b32_e32 v3, v239, v3
	v_xor_b32_e32 v54, v2, v54
	v_xor_b32_e32 v59, v3, v59
	s_cmp_ge_u32 s99, 54
	s_cselect_b32 s98, -1, 0
	v_and_b32_e32 v54, s98, v54
	s_cmp_ge_u32 s99, 55
	s_cselect_b32 s98, -1, 0
	v_and_b32_e32 v59, s98, v59
	v_add_f32_e32 v56, 0, v56
	v_add_f32_e32 v61, 0, v61
	v_ashrrev_i32_e32 v2, 31, v56
	v_ashrrev_i32_e32 v3, 31, v61
	v_or_b32_e32 v2, v239, v2
	v_or_b32_e32 v3, v239, v3
	v_xor_b32_e32 v56, v2, v56
	v_xor_b32_e32 v61, v3, v61
	s_cmp_ge_u32 s99, 56
	s_cselect_b32 s98, -1, 0
	v_and_b32_e32 v56, s98, v56
	s_cmp_ge_u32 s99, 57
	s_cselect_b32 s98, -1, 0
	v_and_b32_e32 v61, s98, v61
	v_add_f32_e32 v58, 0, v58
	v_add_f32_e32 v63, 0, v63
	v_ashrrev_i32_e32 v2, 31, v58
	v_ashrrev_i32_e32 v3, 31, v63
	v_or_b32_e32 v2, v239, v2
	v_or_b32_e32 v3, v239, v3
	v_xor_b32_e32 v58, v2, v58
	v_xor_b32_e32 v63, v3, v63
	s_cmp_ge_u32 s99, 58
	s_cselect_b32 s98, -1, 0
	v_and_b32_e32 v58, s98, v58
	s_cmp_ge_u32 s99, 59
	s_cselect_b32 s98, -1, 0
	v_and_b32_e32 v63, s98, v63
	v_add_f32_e32 v60, 0, v60
	v_add_f32_e32 v64, 0, v64
	v_ashrrev_i32_e32 v2, 31, v60
	v_ashrrev_i32_e32 v3, 31, v64
	v_or_b32_e32 v2, v239, v2
	v_or_b32_e32 v3, v239, v3
	v_xor_b32_e32 v60, v2, v60
	v_xor_b32_e32 v64, v3, v64
	s_cmp_ge_u32 s99, 60
	s_cselect_b32 s98, -1, 0
	v_and_b32_e32 v60, s98, v60
	s_cmp_ge_u32 s99, 61
	s_cselect_b32 s98, -1, 0
	v_and_b32_e32 v64, s98, v64
	v_add_f32_e32 v62, 0, v62
	v_add_f32_e32 v65, 0, v65
	v_ashrrev_i32_e32 v2, 31, v62
	v_ashrrev_i32_e32 v3, 31, v65
	v_or_b32_e32 v2, v239, v2
	v_or_b32_e32 v3, v239, v3
	v_xor_b32_e32 v62, v2, v62
	v_xor_b32_e32 v65, v3, v65
	s_cmp_ge_u32 s99, 62
	s_cselect_b32 s98, -1, 0
	v_and_b32_e32 v62, s98, v62
	s_cmp_ge_u32 s99, 63
	s_cselect_b32 s98, -1, 0
	v_and_b32_e32 v65, s98, v65
	s_branch .Ltk_tf_done
; __device__ __forceinline__ void b1_phase(const bf16* QI, const bf16* KI, const float* WI, float* SCRb  , unsigned long long* MASK,
;                                          LAS unsigned char* lds, int vcu, int G, int tid) {
;     ...
;             for (int j = 0; j < 64; ++j) { unsigned key = 0u; if (j < ntile) { const float f = srow[j * 64] + 0.0f; const unsigned bts = __float_as_uint(f); key = bts ^ ((bts >> 31) ? 0xFFFFFFFFu : 0x80000000u); } uu[j] = key; }
;             unsigned T = 1u;
;             bool exact = (limit <= 256);
;             if (limit > 256) {
;                 unsigned kmax = 0u;
; #pragma unroll
;                 for (int j = 0; j < 64; ++j) kmax = uu[j] > kmax ? uu[j] : kmax;
; #pragma unroll
;                 for (int o = 1; o < 64; o <<= 1) { const unsigned t_ = (unsigned)__shfl_xor((int)kmax, o); kmax = t_ > kmax ? t_ : kmax; }
;                 kmax = (unsigned)__builtin_amdgcn_readfirstlane((int)kmax);
;                 unsigned a = 1u, b = kmax + 1u; if (b == 0u) b = 0xFFFFFFFFu;
;                 float fa = (float)(limit - 256) + 0.5f, fb = -255.5f; int side = 0;
;                 bool done = false;
;                 if (b > 0x80000001u) {
;                     unsigned l0 = 0u, l1 = 0u, l2 = 0u, l3 = 0u; const unsigned csign = 0x80000000u;
; #pragma unroll
;                     for (int j = 0; j < 64; j += 4) cnt_lt4(l0, l1, l2, l3, uu[j], uu[j + 1], uu[j + 2], uu[j + 3], csign);
.Ltk_zero_1:
	v_mov_b32_e32 v16, 0
	v_mov_b32_e32 v20, 0
	v_mov_b32_e32 v19, 0
	v_mov_b32_e32 v22, 0
	v_mov_b32_e32 v21, 0
	v_mov_b32_e32 v24, 0
	v_mov_b32_e32 v23, 0
	v_mov_b32_e32 v26, 0
	v_mov_b32_e32 v25, 0
	v_mov_b32_e32 v28, 0
	v_mov_b32_e32 v27, 0
	v_mov_b32_e32 v30, 0
	v_mov_b32_e32 v29, 0
	v_mov_b32_e32 v32, 0
	v_mov_b32_e32 v31, 0
	v_mov_b32_e32 v34, 0
.Ltk_zero_2:
	v_mov_b32_e32 v33, 0
	v_mov_b32_e32 v37, 0
	v_mov_b32_e32 v35, 0
	v_mov_b32_e32 v39, 0
	v_mov_b32_e32 v36, 0
	v_mov_b32_e32 v41, 0
	v_mov_b32_e32 v38, 0
	v_mov_b32_e32 v43, 0
	v_mov_b32_e32 v40, 0
	v_mov_b32_e32 v45, 0
	v_mov_b32_e32 v42, 0
	v_mov_b32_e32 v47, 0
	v_mov_b32_e32 v44, 0
	v_mov_b32_e32 v49, 0
	v_mov_b32_e32 v46, 0
	v_mov_b32_e32 v51, 0
.Ltk_zero_3:
	v_mov_b32_e32 v48, 0
	v_mov_b32_e32 v53, 0
	v_mov_b32_e32 v50, 0
	v_mov_b32_e32 v55, 0
	v_mov_b32_e32 v52, 0
	v_mov_b32_e32 v57, 0
	v_mov_b32_e32 v54, 0
	v_mov_b32_e32 v59, 0
	v_mov_b32_e32 v56, 0
	v_mov_b32_e32 v61, 0
	v_mov_b32_e32 v58, 0
	v_mov_b32_e32 v63, 0
	v_mov_b32_e32 v60, 0
	v_mov_b32_e32 v64, 0
	v_mov_b32_e32 v62, 0
	v_mov_b32_e32 v65, 0
.Ltk_tf_done:
.LBB0_661:
	s_waitcnt vmcnt(0)
	v_add_f32_e32 v2, 0, v66
	v_cmp_lt_i32_e32 vcc, -1, v2
	v_readlane_b32 s0, v251, 12
	v_mov_b32_e32 v66, 1
	v_cndmask_b32_e32 v3, -1, v239, vcc
	v_xor_b32_e32 v67, v3, v2
	s_and_b64 vcc, exec, s[6:7]
	v_readlane_b32 s1, v251, 13
	s_cbranch_vccz .LBB0_666
	v_max_u32_e32 v2, v6, v67
	v_max3_u32 v2, v8, v0, v2
	v_max3_u32 v2, v10, v4, v2
	v_max3_u32 v2, v12, v5, v2
	v_max3_u32 v2, v14, v7, v2
	v_max3_u32 v2, v15, v9, v2
	v_max3_u32 v2, v17, v11, v2
	v_max3_u32 v2, v18, v13, v2
	v_max3_u32 v2, v20, v16, v2
	v_max3_u32 v2, v22, v19, v2
	v_max3_u32 v2, v24, v21, v2
	v_max3_u32 v2, v26, v23, v2
	v_max3_u32 v2, v28, v25, v2
	v_max3_u32 v2, v30, v27, v2
	v_max3_u32 v2, v32, v29, v2
	v_max3_u32 v2, v34, v31, v2
	v_max3_u32 v2, v37, v33, v2
	v_max3_u32 v2, v39, v35, v2
	v_max3_u32 v2, v41, v36, v2
	v_max3_u32 v2, v43, v38, v2
	v_max3_u32 v2, v45, v40, v2
	v_max3_u32 v2, v47, v42, v2
	v_max3_u32 v2, v49, v44, v2
	v_max3_u32 v2, v51, v46, v2
	v_max3_u32 v2, v53, v48, v2
	v_max3_u32 v2, v55, v50, v2
	v_max3_u32 v2, v57, v52, v2
	v_max3_u32 v2, v59, v54, v2
	v_and_b32_e32 v3, 64, v238
	v_max3_u32 v2, v61, v56, v2
	v_add_u32_e32 v3, 64, v3
	v_xor_b32_e32 v66, 1, v238
	v_max3_u32 v2, v63, v58, v2
	v_cmp_lt_i32_e32 vcc, v66, v3
	v_max3_u32 v2, v64, v60, v2
	v_max3_u32 v2, v65, v62, v2
	v_cndmask_b32_e32 v66, v238, v66, vcc
	v_lshlrev_b32_e32 v66, 2, v66
	ds_bpermute_b32 v66, v66, v2
	s_mov_b32 s4, 1
	s_waitcnt lgkmcnt(0)
	v_max_u32_e32 v2, v66, v2
	v_xor_b32_e32 v66, 2, v238
	v_cmp_lt_i32_e32 vcc, v66, v3
	s_nop 1
	v_cndmask_b32_e32 v66, v238, v66, vcc
	v_lshlrev_b32_e32 v66, 2, v66
	ds_bpermute_b32 v66, v66, v2
	s_waitcnt lgkmcnt(0)
	v_max_u32_e32 v2, v66, v2
	v_xor_b32_e32 v66, 4, v238
	v_cmp_lt_i32_e32 vcc, v66, v3
	s_nop 1
	v_cndmask_b32_e32 v66, v238, v66, vcc
	v_lshlrev_b32_e32 v66, 2, v66
	ds_bpermute_b32 v66, v66, v2
	s_waitcnt lgkmcnt(0)
	v_max_u32_e32 v2, v66, v2
	v_xor_b32_e32 v66, 8, v238
	v_cmp_lt_i32_e32 vcc, v66, v3
	s_nop 1
	v_cndmask_b32_e32 v66, v238, v66, vcc
	v_lshlrev_b32_e32 v66, 2, v66
	ds_bpermute_b32 v66, v66, v2
	s_waitcnt lgkmcnt(0)
	v_max_u32_e32 v2, v66, v2
	v_xor_b32_e32 v66, 16, v238
	v_cmp_lt_i32_e32 vcc, v66, v3
	s_nop 1
	v_cndmask_b32_e32 v66, v238, v66, vcc
	v_lshlrev_b32_e32 v66, 2, v66
	ds_bpermute_b32 v66, v66, v2
	s_waitcnt lgkmcnt(0)
	v_max_u32_e32 v2, v66, v2
	v_xor_b32_e32 v66, 32, v238
	v_cmp_lt_i32_e32 vcc, v66, v3
	s_nop 1
	v_cndmask_b32_e32 v3, v238, v66, vcc
	v_lshlrev_b32_e32 v3, 2, v3
	ds_bpermute_b32 v3, v3, v2
	s_waitcnt lgkmcnt(0)
	v_max_u32_e32 v2, v3, v2
	s_nop 0
	v_readfirstlane_b32 s0, v2
	s_nop 1
	v_add_co_u32_e64 v3, s[0:1], s0, 1
	s_nop 1
	v_cndmask_b32_e64 v66, v3, -1, s[0:1]
	s_mov_b32 s0, 0x80000001
	v_cmp_lt_u32_e32 vcc, s0, v66
	s_cbranch_vccz .LBB0_668
	s_lshr_b32 s98, s99, 4
	s_lshl_b32 s98, s98, 4
	s_sub_u32 s98, 48, s98
	v_mov_b32_e32 v2, s98
	v_mov_b32_e32 v3, v1
	v_mov_b32_e32 v68, v1
	v_mov_b32_e32 v69, v1
	v_cmp_lt_u32_e64 s[0:1], v67, v239
	v_cmp_lt_u32_e64 s[2:3], v6, v239
	v_cmp_lt_u32_e64 s[4:5], v0, v239
	v_cmp_lt_u32_e64 s[6:7], v8, v239
	v_addc_co_u32_e64 v2, s[0:1], v2, 0, s[0:1]
	v_addc_co_u32_e64 v3, s[2:3], v3, 0, s[2:3]
	v_addc_co_u32_e64 v68, s[4:5], v68, 0, s[4:5]
	v_addc_co_u32_e64 v69, s[6:7], v69, 0, s[6:7]
	s_nop 0
	v_cmp_lt_u32_e64 s[0:1], v4, v239
	v_cmp_lt_u32_e64 s[2:3], v10, v239
	v_cmp_lt_u32_e64 s[4:5], v5, v239
	v_cmp_lt_u32_e64 s[6:7], v12, v239
	v_addc_co_u32_e64 v2, s[0:1], v2, 0, s[0:1]
	v_addc_co_u32_e64 v3, s[2:3], v3, 0, s[2:3]
	v_addc_co_u32_e64 v68, s[4:5], v68, 0, s[4:5]
	v_addc_co_u32_e64 v69, s[6:7], v69, 0, s[6:7]
	s_nop 0
	v_cmp_lt_u32_e64 s[0:1], v7, v239
	v_cmp_lt_u32_e64 s[2:3], v14, v239
	v_cmp_lt_u32_e64 s[4:5], v9, v239
	v_cmp_lt_u32_e64 s[6:7], v15, v239
	v_addc_co_u32_e64 v2, s[0:1], v2, 0, s[0:1]
	v_addc_co_u32_e64 v3, s[2:3], v3, 0, s[2:3]
	v_addc_co_u32_e64 v68, s[4:5], v68, 0, s[4:5]
	v_addc_co_u32_e64 v69, s[6:7], v69, 0, s[6:7]
	s_nop 0
	v_cmp_lt_u32_e64 s[0:1], v11, v239
	v_cmp_lt_u32_e64 s[2:3], v17, v239
	v_cmp_lt_u32_e64 s[4:5], v13, v239
	v_cmp_lt_u32_e64 s[6:7], v18, v239
	v_addc_co_u32_e64 v2, s[0:1], v2, 0, s[0:1]
	v_addc_co_u32_e64 v3, s[2:3], v3, 0, s[2:3]
	v_addc_co_u32_e64 v68, s[4:5], v68, 0, s[4:5]
	v_addc_co_u32_e64 v69, s[6:7], v69, 0, s[6:7]
	s_nop 0
	s_cmp_lt_u32 s99, 16
	s_cbranch_scc1 .Ltk_red_sign
; __device__ __forceinline__ void b1_phase(const bf16* QI, const bf16* KI, const float* WI, float* SCRb  , unsigned long long* MASK,
;                                          LAS unsigned char* lds, int vcu, int G, int tid) {
;     ...
;                     unsigned l0 = 0u, l1 = 0u, l2 = 0u, l3 = 0u; const unsigned csign = 0x80000000u;
; #pragma unroll
;                     for (int j = 0; j < 64; j += 4) cnt_lt4(l0, l1, l2, l3, uu[j], uu[j + 1], uu[j + 2], uu[j + 3], csign);
;                     const unsigned less = (l0 + l1) + (l2 + l3);
	v_cmp_lt_u32_e64 s[0:1], v16, v239
	v_cmp_lt_u32_e64 s[2:3], v20, v239
	v_cmp_lt_u32_e64 s[4:5], v19, v239
	v_cmp_lt_u32_e64 s[6:7], v22, v239
	v_addc_co_u32_e64 v2, s[0:1], v2, 0, s[0:1]
	v_addc_co_u32_e64 v3, s[2:3], v3, 0, s[2:3]
	v_addc_co_u32_e64 v68, s[4:5], v68, 0, s[4:5]
	v_addc_co_u32_e64 v69, s[6:7], v69, 0, s[6:7]
	s_nop 0
	v_cmp_lt_u32_e64 s[0:1], v21, v239
	v_cmp_lt_u32_e64 s[2:3], v24, v239
	v_cmp_lt_u32_e64 s[4:5], v23, v239
	v_cmp_lt_u32_e64 s[6:7], v26, v239
	v_addc_co_u32_e64 v2, s[0:1], v2, 0, s[0:1]
	v_addc_co_u32_e64 v3, s[2:3], v3, 0, s[2:3]
	v_addc_co_u32_e64 v68, s[4:5], v68, 0, s[4:5]
	v_addc_co_u32_e64 v69, s[6:7], v69, 0, s[6:7]
	s_nop 0
	v_cmp_lt_u32_e64 s[0:1], v25, v239
	v_cmp_lt_u32_e64 s[2:3], v28, v239
	v_cmp_lt_u32_e64 s[4:5], v27, v239
	v_cmp_lt_u32_e64 s[6:7], v30, v239
	v_addc_co_u32_e64 v2, s[0:1], v2, 0, s[0:1]
	v_addc_co_u32_e64 v3, s[2:3], v3, 0, s[2:3]
	v_addc_co_u32_e64 v68, s[4:5], v68, 0, s[4:5]
	v_addc_co_u32_e64 v69, s[6:7], v69, 0, s[6:7]
	s_nop 0
	v_cmp_lt_u32_e64 s[0:1], v29, v239
	v_cmp_lt_u32_e64 s[2:3], v32, v239
	v_cmp_lt_u32_e64 s[4:5], v31, v239
	v_cmp_lt_u32_e64 s[6:7], v34, v239
	v_addc_co_u32_e64 v2, s[0:1], v2, 0, s[0:1]
	v_addc_co_u32_e64 v3, s[2:3], v3, 0, s[2:3]
	v_addc_co_u32_e64 v68, s[4:5], v68, 0, s[4:5]
	v_addc_co_u32_e64 v69, s[6:7], v69, 0, s[6:7]
	s_nop 0
	s_cmp_lt_u32 s99, 32
	s_cbranch_scc1 .Ltk_red_sign
	v_cmp_lt_u32_e64 s[0:1], v33, v239
	v_cmp_lt_u32_e64 s[2:3], v37, v239
	v_cmp_lt_u32_e64 s[4:5], v35, v239
	v_cmp_lt_u32_e64 s[6:7], v39, v239
	v_addc_co_u32_e64 v2, s[0:1], v2, 0, s[0:1]
	v_addc_co_u32_e64 v3, s[2:3], v3, 0, s[2:3]
	v_addc_co_u32_e64 v68, s[4:5], v68, 0, s[4:5]
	v_addc_co_u32_e64 v69, s[6:7], v69, 0, s[6:7]
	s_nop 0
	v_cmp_lt_u32_e64 s[0:1], v36, v239
	v_cmp_lt_u32_e64 s[2:3], v41, v239
	v_cmp_lt_u32_e64 s[4:5], v38, v239
	v_cmp_lt_u32_e64 s[6:7], v43, v239
	v_addc_co_u32_e64 v2, s[0:1], v2, 0, s[0:1]
	v_addc_co_u32_e64 v3, s[2:3], v3, 0, s[2:3]
	v_addc_co_u32_e64 v68, s[4:5], v68, 0, s[4:5]
	v_addc_co_u32_e64 v69, s[6:7], v69, 0, s[6:7]
	s_nop 0
	v_cmp_lt_u32_e64 s[0:1], v40, v239
	v_cmp_lt_u32_e64 s[2:3], v45, v239
	v_cmp_lt_u32_e64 s[4:5], v42, v239
	v_cmp_lt_u32_e64 s[6:7], v47, v239
	v_addc_co_u32_e64 v2, s[0:1], v2, 0, s[0:1]
	v_addc_co_u32_e64 v3, s[2:3], v3, 0, s[2:3]
	v_addc_co_u32_e64 v68, s[4:5], v68, 0, s[4:5]
	v_addc_co_u32_e64 v69, s[6:7], v69, 0, s[6:7]
	s_nop 0
	v_cmp_lt_u32_e64 s[0:1], v44, v239
	v_cmp_lt_u32_e64 s[2:3], v49, v239
	v_cmp_lt_u32_e64 s[4:5], v46, v239
	v_cmp_lt_u32_e64 s[6:7], v51, v239
	v_addc_co_u32_e64 v2, s[0:1], v2, 0, s[0:1]
	v_addc_co_u32_e64 v3, s[2:3], v3, 0, s[2:3]
	v_addc_co_u32_e64 v68, s[4:5], v68, 0, s[4:5]
	v_addc_co_u32_e64 v69, s[6:7], v69, 0, s[6:7]
	s_nop 0
	s_cmp_lt_u32 s99, 48
	s_cbranch_scc1 .Ltk_red_sign
	v_cmp_lt_u32_e64 s[0:1], v48, v239
	v_cmp_lt_u32_e64 s[2:3], v53, v239
	v_cmp_lt_u32_e64 s[4:5], v50, v239
	v_cmp_lt_u32_e64 s[6:7], v55, v239
	v_addc_co_u32_e64 v2, s[0:1], v2, 0, s[0:1]
	v_addc_co_u32_e64 v3, s[2:3], v3, 0, s[2:3]
	v_addc_co_u32_e64 v68, s[4:5], v68, 0, s[4:5]
	v_addc_co_u32_e64 v69, s[6:7], v69, 0, s[6:7]
	s_nop 0
	v_cmp_lt_u32_e64 s[0:1], v52, v239
	v_cmp_lt_u32_e64 s[2:3], v57, v239
	v_cmp_lt_u32_e64 s[4:5], v54, v239
	v_cmp_lt_u32_e64 s[6:7], v59, v239
	v_addc_co_u32_e64 v2, s[0:1], v2, 0, s[0:1]
	v_addc_co_u32_e64 v3, s[2:3], v3, 0, s[2:3]
	v_addc_co_u32_e64 v68, s[4:5], v68, 0, s[4:5]
	v_addc_co_u32_e64 v69, s[6:7], v69, 0, s[6:7]
	s_nop 0
	v_cmp_lt_u32_e64 s[0:1], v56, v239
	v_cmp_lt_u32_e64 s[2:3], v61, v239
	v_cmp_lt_u32_e64 s[4:5], v58, v239
	v_cmp_lt_u32_e64 s[6:7], v63, v239
	v_addc_co_u32_e64 v2, s[0:1], v2, 0, s[0:1]
	v_addc_co_u32_e64 v3, s[2:3], v3, 0, s[2:3]
	v_addc_co_u32_e64 v68, s[4:5], v68, 0, s[4:5]
	v_addc_co_u32_e64 v69, s[6:7], v69, 0, s[6:7]
	s_nop 0
	v_cmp_lt_u32_e64 s[0:1], v60, v239
	v_cmp_lt_u32_e64 s[2:3], v64, v239
	v_cmp_lt_u32_e64 s[4:5], v62, v239
	v_cmp_lt_u32_e64 s[6:7], v65, v239
	v_addc_co_u32_e64 v2, s[0:1], v2, 0, s[0:1]
	v_addc_co_u32_e64 v3, s[2:3], v3, 0, s[2:3]
	v_addc_co_u32_e64 v68, s[4:5], v68, 0, s[4:5]
	v_addc_co_u32_e64 v69, s[6:7], v69, 0, s[6:7]

; #define MASK WSL(unsigned long long, WS_MASK)
; __device__ __forceinline__ void b1_phase(const bf16* QI, const bf16* KI, const float* WI, float* SCRb  , unsigned long long* MASK,
;                                          LAS unsigned char* lds, int vcu, int G, int tid) {
;     ...
;             unsigned long long myword = 0ull;
;             if (exact) {
; #pragma unroll
;                 for (int j = 0; j < 64; ++j) { const unsigned long long word = __ballot(uu[j] >= T); if (lane == j) myword = word; }
;     ...
;             if (lane < ntile) MASK[(tok0 + q) * 64 + lane] = myword;
.LBB0_686:
	v_cmp_ge_u32_e64 s[0:1], v67, v66
	v_cmp_ge_u32_e64 s[2:3], v6, v66
	v_cmp_ge_u32_e64 s[4:5], v0, v66
	v_cmp_ge_u32_e64 s[8:9], v8, v66
	v_writelane_b32 v2, s0, 0
	v_writelane_b32 v3, s1, 0
	v_writelane_b32 v2, s2, 1
	v_writelane_b32 v3, s3, 1
	v_writelane_b32 v2, s4, 2
	v_writelane_b32 v3, s5, 2
	v_writelane_b32 v2, s8, 3
	v_writelane_b32 v3, s9, 3
	v_cmp_ge_u32_e64 s[0:1], v4, v66
	v_cmp_ge_u32_e64 s[2:3], v10, v66
	v_cmp_ge_u32_e64 s[4:5], v5, v66
	v_cmp_ge_u32_e64 s[8:9], v12, v66
	v_writelane_b32 v2, s0, 4
	v_writelane_b32 v3, s1, 4
	v_writelane_b32 v2, s2, 5
	v_writelane_b32 v3, s3, 5
	v_writelane_b32 v2, s4, 6
	v_writelane_b32 v3, s5, 6
	v_writelane_b32 v2, s8, 7
	v_writelane_b32 v3, s9, 7
	v_cmp_ge_u32_e64 s[0:1], v7, v66
	v_cmp_ge_u32_e64 s[2:3], v14, v66
	v_cmp_ge_u32_e64 s[4:5], v9, v66
	v_cmp_ge_u32_e64 s[8:9], v15, v66
	v_writelane_b32 v2, s0, 8
	v_writelane_b32 v3, s1, 8
	v_writelane_b32 v2, s2, 9
	v_writelane_b32 v3, s3, 9
	v_writelane_b32 v2, s4, 10
	v_writelane_b32 v3, s5, 10
	v_writelane_b32 v2, s8, 11
	v_writelane_b32 v3, s9, 11
	v_cmp_ge_u32_e64 s[0:1], v11, v66
	v_cmp_ge_u32_e64 s[2:3], v17, v66
	v_cmp_ge_u32_e64 s[4:5], v13, v66
	v_cmp_ge_u32_e64 s[8:9], v18, v66
	v_writelane_b32 v2, s0, 12
	v_writelane_b32 v3, s1, 12
	v_writelane_b32 v2, s2, 13
	v_writelane_b32 v3, s3, 13
	v_writelane_b32 v2, s4, 14
	v_writelane_b32 v3, s5, 14
	v_writelane_b32 v2, s8, 15
	v_writelane_b32 v3, s9, 15
	s_cmp_lt_u32 s99, 16
	s_cbranch_scc1 .LBB0_687
	v_cmp_ge_u32_e64 s[0:1], v16, v66
	v_cmp_ge_u32_e64 s[2:3], v20, v66
	v_cmp_ge_u32_e64 s[4:5], v19, v66
	v_cmp_ge_u32_e64 s[8:9], v22, v66
	v_writelane_b32 v2, s0, 16
	v_writelane_b32 v3, s1, 16
	v_writelane_b32 v2, s2, 17
	v_writelane_b32 v3, s3, 17
	v_writelane_b32 v2, s4, 18
	v_writelane_b32 v3, s5, 18
	v_writelane_b32 v2, s8, 19
	v_writelane_b32 v3, s9, 19
	v_cmp_ge_u32_e64 s[0:1], v21, v66
	v_cmp_ge_u32_e64 s[2:3], v24, v66
	v_cmp_ge_u32_e64 s[4:5], v23, v66
	v_cmp_ge_u32_e64 s[8:9], v26, v66
	v_writelane_b32 v2, s0, 20
	v_writelane_b32 v3, s1, 20
	v_writelane_b32 v2, s2, 21
	v_writelane_b32 v3, s3, 21
	v_writelane_b32 v2, s4, 22
	v_writelane_b32 v3, s5, 22
	v_writelane_b32 v2, s8, 23
	v_writelane_b32 v3, s9, 23
	v_cmp_ge_u32_e64 s[0:1], v25, v66
	v_cmp_ge_u32_e64 s[2:3], v28, v66
	v_cmp_ge_u32_e64 s[4:5], v27, v66
	v_cmp_ge_u32_e64 s[8:9], v30, v66
	v_writelane_b32 v2, s0, 24
	v_writelane_b32 v3, s1, 24
	v_writelane_b32 v2, s2, 25
	v_writelane_b32 v3, s3, 25
	v_writelane_b32 v2, s4, 26
	v_writelane_b32 v3, s5, 26
	v_writelane_b32 v2, s8, 27
	v_writelane_b32 v3, s9, 27
	v_cmp_ge_u32_e64 s[0:1], v29, v66
	v_cmp_ge_u32_e64 s[2:3], v32, v66
	v_cmp_ge_u32_e64 s[4:5], v31, v66
	v_cmp_ge_u32_e64 s[8:9], v34, v66
	v_writelane_b32 v2, s0, 28
	v_writelane_b32 v3, s1, 28
	v_writelane_b32 v2, s2, 29
	v_writelane_b32 v3, s3, 29
	v_writelane_b32 v2, s4, 30
	v_writelane_b32 v3, s5, 30
	v_writelane_b32 v2, s8, 31
	v_writelane_b32 v3, s9, 31
	s_cmp_lt_u32 s99, 32
	s_cbranch_scc1 .LBB0_687
	v_cmp_ge_u32_e64 s[0:1], v33, v66
	v_cmp_ge_u32_e64 s[2:3], v37, v66
	v_cmp_ge_u32_e64 s[4:5], v35, v66
	v_cmp_ge_u32_e64 s[8:9], v39, v66
	v_writelane_b32 v2, s0, 32
	v_writelane_b32 v3, s1, 32
	v_writelane_b32 v2, s2, 33
	v_writelane_b32 v3, s3, 33
	v_writelane_b32 v2, s4, 34
	v_writelane_b32 v3, s5, 34
	v_writelane_b32 v2, s8, 35
	v_writelane_b32 v3, s9, 35
	v_cmp_ge_u32_e64 s[0:1], v36, v66
	v_cmp_ge_u32_e64 s[2:3], v41, v66
	v_cmp_ge_u32_e64 s[4:5], v38, v66
	v_cmp_ge_u32_e64 s[8:9], v43, v66
	v_writelane_b32 v2, s0, 36
	v_writelane_b32 v3, s1, 36
	v_writelane_b32 v2, s2, 37
	v_writelane_b32 v3, s3, 37
	v_writelane_b32 v2, s4, 38
	v_writelane_b32 v3, s5, 38
	v_writelane_b32 v2, s8, 39
	v_writelane_b32 v3, s9, 39
	v_cmp_ge_u32_e64 s[0:1], v40, v66
	v_cmp_ge_u32_e64 s[2:3], v45, v66
	v_cmp_ge_u32_e64 s[4:5], v42, v66
	v_cmp_ge_u32_e64 s[8:9], v47, v66
	v_writelane_b32 v2, s0, 40
	v_writelane_b32 v3, s1, 40
	v_writelane_b32 v2, s2, 41
	v_writelane_b32 v3, s3, 41
	v_writelane_b32 v2, s4, 42
	v_writelane_b32 v3, s5, 42
	v_writelane_b32 v2, s8, 43
	v_writelane_b32 v3, s9, 43
	v_cmp_ge_u32_e64 s[0:1], v44, v66
	v_cmp_ge_u32_e64 s[2:3], v49, v66
	v_cmp_ge_u32_e64 s[4:5], v46, v66
	v_cmp_ge_u32_e64 s[8:9], v51, v66
	v_writelane_b32 v2, s0, 44
	v_writelane_b32 v3, s1, 44
	v_writelane_b32 v2, s2, 45
	v_writelane_b32 v3, s3, 45
	v_writelane_b32 v2, s4, 46
	v_writelane_b32 v3, s5, 46
	v_writelane_b32 v2, s8, 47
	v_writelane_b32 v3, s9, 47
	s_cmp_lt_u32 s99, 48
	s_cbranch_scc1 .LBB0_687
	v_cmp_ge_u32_e64 s[0:1], v48, v66
	v_cmp_ge_u32_e64 s[2:3], v53, v66
	v_cmp_ge_u32_e64 s[4:5], v50, v66
	v_cmp_ge_u32_e64 s[8:9], v55, v66
	v_writelane_b32 v2, s0, 48
	v_writelane_b32 v3, s1, 48
	v_writelane_b32 v2, s2, 49
	v_writelane_b32 v3, s3, 49
	v_writelane_b32 v2, s4, 50
	v_writelane_b32 v3, s5, 50
	v_writelane_b32 v2, s8, 51
	v_writelane_b32 v3, s9, 51
	v_cmp_ge_u32_e64 s[0:1], v52, v66
	v_cmp_ge_u32_e64 s[2:3], v57, v66
	v_cmp_ge_u32_e64 s[4:5], v54, v66
	v_cmp_ge_u32_e64 s[8:9], v59, v66
	v_writelane_b32 v2, s0, 52
	v_writelane_b32 v3, s1, 52
	v_writelane_b32 v2, s2, 53
	v_writelane_b32 v3, s3, 53
	v_writelane_b32 v2, s4, 54
	v_writelane_b32 v3, s5, 54
	v_writelane_b32 v2, s8, 55
	v_writelane_b32 v3, s9, 55
	v_cmp_ge_u32_e64 s[0:1], v56, v66
	v_cmp_ge_u32_e64 s[2:3], v61, v66
	v_cmp_ge_u32_e64 s[4:5], v58, v66
	v_cmp_ge_u32_e64 s[8:9], v63, v66
	v_writelane_b32 v2, s0, 56
	v_writelane_b32 v3, s1, 56
	v_writelane_b32 v2, s2, 57
	v_writelane_b32 v3, s3, 57
	v_writelane_b32 v2, s4, 58
	v_writelane_b32 v3, s5, 58
	v_writelane_b32 v2, s8, 59
	v_writelane_b32 v3, s9, 59
	v_cmp_ge_u32_e64 s[0:1], v60, v66
	v_cmp_ge_u32_e64 s[2:3], v64, v66
	v_cmp_ge_u32_e64 s[4:5], v62, v66
	v_cmp_ge_u32_e64 s[8:9], v65, v66
	v_writelane_b32 v2, s0, 60
	v_writelane_b32 v3, s1, 60
	v_writelane_b32 v2, s2, 61
	v_writelane_b32 v3, s3, 61
	v_writelane_b32 v2, s4, 62
	v_writelane_b32 v3, s5, 62
	v_writelane_b32 v2, s8, 63
	v_writelane_b32 v3, s9, 63
